# att V-transpose staging loads batched; scan WGs take 3 conversion tiles in their slack
# baseline (speedup 1.0000x reference)
; __global__ void __launch_bounds__(NWAVES * 64, 2) mega_fwd(Args A) {
;     ...
;     for (int step = 0; step < 3 * DEPTH; ++step) {
;         const int l = step / 3, kind = step - 3 * l;
;         unsigned char* wl = ws + WS_W + (size_t)l * LW_END;
;         const unsigned long long* ssq = (const unsigned long long*)(ws + WS_CTL + CTL_SSQ) + (size_t)step * NTOK; unsigned long long* ssq_next = (unsigned long long*)(ws + WS_CTL + CTL_SSQ) + (size_t)(step + 1) * NTOK;
;         if (kind != 1) {
;             { pg8::Gemm g{H, (const bf16*)(wl + (kind == 0 ? LW_WI1 : LW_WI2)), NTOK, NWI, DM}; pg8::StaticOrder S; S.init(NTOK, NWI, G, bx);
;               pg8::EpiSwiglu E{ACT, DFF, ssq};
;               pg8::gemm_phase<pg8::EpiSwiglu, pg8::StaticOrder, true, true>(lds + RING_OFF, g, S, E); }
;             { const int rem1 = ((NTOK / 256) * (NWI / 256)) % G;
;               conv_until(A, lds, l * TL_LAYER + (kind == 0 ? TL_WIN : TL_LAYER), (rem1 != 0 && bx >= rem1) ? 3 : 0); }
;             xcd_barrier(bar);
;         } else {
;             const bool std256 = (G == 256);
;             unsigned char* XB8 = ws + WS_X;
; #pragma unroll 1
;             for (int part = 0; part < 3; ++part) {
;                 bool do16, do8; int i16, n16, g8, c8, i8, n8;
;                 if (std256) { do16 = part == 0 || (part == 1 && bx < 64); i16 = part ? 2 : 0; n16 = part ? 1 : 2;
;                               do8 = (part == 1 && bx >= 64) || (part == 2 && bx < 128); g8 = part == 1 ? 192 : 128; c8 = part == 1 ? bx - 64 : bx; i8 = part == 1 ? 0 : 3; n8 = part == 1 ? 2 : 3; }
;                 else { do16 = part == 0; i16 = 0; n16 = 1 << 20; do8 = part == 1; g8 = G; c8 = bx; i8 = 0; n8 = 1 << 20; }
;                 if (do16) { pg8::Gemm g{H, (const bf16*)(wl + LW_WIN), NTOK, C_GATE, DM}; pg8::RangeOrder S; S.init(NTOK, C_GATE, G, bx); S.i0 = i16; S.n = n16;
;                     pg8::EpiProj E{PROJ, NPROJ, (const float*)A.in[7] + (size_t)l * 6144, 1 << 20, ssq, 1.0f};
;                     pg8::gemm_phase<pg8::EpiProj, pg8::RangeOrder, true, true>(lds + RING_OFF, g, S, E); }
;                 if (do8) { pg8::Gemm g{(const bf16*)XB8, (const bf16*)(wl + LW_WIN + WIN8_OFF), NTOK, 6144, DM / 2}; pg8::RangeOrder S; S.init(NTOK, 6144, g8, c8); S.i0 = i8; S.n = n8;
.LBB0_284:
	v_writelane_b32 v252, s64, 42
	s_nop 1
	v_writelane_b32 v252, s65, 43
	v_writelane_b32 v252, s66, 44
	v_writelane_b32 v252, s67, 45
	v_writelane_b32 v252, s68, 46
	v_writelane_b32 v252, s69, 47
	v_writelane_b32 v252, s70, 48
	v_writelane_b32 v252, s71, 49
	v_writelane_b32 v252, s72, 50
	v_writelane_b32 v252, s73, 51
	v_writelane_b32 v252, s74, 52
	v_writelane_b32 v252, s75, 53
	v_writelane_b32 v252, s76, 54
	v_writelane_b32 v252, s77, 55
	v_writelane_b32 v252, s78, 56
	v_writelane_b32 v252, s79, 57
	s_or_b64 exec, exec, s[0:1]
	s_cmpk_lg_i32 s95, 0x100
	s_cselect_b64 s[0:1], -1, 0
	s_and_b64 s[0:1], s[0:1], exec
	s_cselect_b32 s69, s95, 0x80
	s_add_i32 s4, s97, 0xffffff80
	s_cmpk_lg_i32 s95, 0x100
	s_cselect_b64 s[0:1], -1, 0
	s_and_b64 s[2:3], s[0:1], exec
	s_cselect_b32 s20, s97, s4
	v_readlane_b32 s4, v252, 2
	v_readlane_b32 s18, v252, 16
	v_readlane_b32 s19, v252, 17
	s_add_u32 s74, s18, 0x10000
	s_addc_u32 s2, s19, 0
	v_readlane_b32 s5, v252, 3
	v_readlane_b32 s6, v252, 4
	v_readlane_b32 s7, v252, 5
	v_readlane_b32 s8, v252, 6
	v_readlane_b32 s9, v252, 7
	v_readlane_b32 s10, v252, 8
	v_readlane_b32 s11, v252, 9
	v_readlane_b32 s12, v252, 10
	v_readlane_b32 s13, v252, 11
	v_readlane_b32 s14, v252, 12
	v_readlane_b32 s15, v252, 13
	v_readlane_b32 s16, v252, 14
	v_readlane_b32 s17, v252, 15
	v_writelane_b32 v252, s2, 58
	s_add_u32 s2, s18, 0x35e00000
	s_addc_u32 s3, s19, 0
	s_add_u32 s88, s18, 0x3b600000
	s_addc_u32 s89, s19, 0
	v_writelane_b32 v252, s2, 59
	s_add_u32 s12, s18, 0x45e00000
	s_addc_u32 s13, s19, 0
	v_writelane_b32 v252, s3, 60
	v_writelane_b32 v252, s12, 61
	s_add_u32 s2, s18, 0x4c200000
	v_writelane_b32 v252, s13, 62
	s_addc_u32 s3, s19, 0
	v_writelane_b32 v252, s2, 63
	s_waitcnt vmcnt(15)
	v_mov_b32_e32 v3, 0
	v_mov_b32_e32 v216, 1
	v_writelane_b32 v253, s3, 0
	s_add_u32 s2, s18, 0x4e200000
	s_addc_u32 s3, s19, 0
	v_writelane_b32 v253, s2, 1
	v_mov_b32_e32 v217, 0x7f7f7f7f
	v_mov_b32_e32 v225, 0x43e00000
	v_writelane_b32 v253, s3, 2
	s_add_u32 s2, s18, 0x4fa00000
	s_addc_u32 s3, s19, 0
	v_writelane_b32 v253, s2, 3
	v_mov_b64_e32 v[226:227], 0x2ff
	v_mov_b32_e32 v222, 0x41b17218
	v_writelane_b32 v253, s3, 4
	s_add_u32 s2, s18, 0x4fb00000
	s_addc_u32 s3, s19, 0
	v_writelane_b32 v253, s2, 5
	v_mbcnt_hi_u32_b32 v223, -1, v76
	v_mov_b32_e32 v224, 0xf149f2ca
	v_writelane_b32 v253, s3, 6
	s_add_u32 s2, s18, 0x200000
	v_writelane_b32 v253, s2, 7
	s_addc_u32 s2, s19, 0
	s_cmpk_lt_i32 s97, 0x580
	v_writelane_b32 v253, s2, 8
	s_cselect_b64 s[2:3], -1, 0
	v_writelane_b32 v253, s2, 9
	s_ashr_i32 s21, s97, 31
	s_movk_i32 s75, 0xc0
	v_writelane_b32 v253, s3, 10
	s_lshr_b32 s2, s21, 29
	s_add_i32 s3, s97, s2
	s_ashr_i32 s2, s3, 3
	s_and_b32 s3, s3, -8
	s_sub_i32 s5, s97, s3
	s_ashr_i32 s3, s95, 31
	s_add_u32 s6, s18, 0x4200
	v_writelane_b32 v253, s3, 11
	s_addc_u32 s7, s19, 0
	v_writelane_b32 v253, s6, 12
	s_movk_i32 s76, 0x300
	s_movk_i32 s77, 0x5400
	v_writelane_b32 v253, s7, 13
	s_add_u32 s6, s18, 0x4400
	s_addc_u32 s7, s19, 0
	v_writelane_b32 v253, s6, 14
	s_movk_i32 s81, 0x7fff
	s_mov_b32 s82, 0xffff0000
	v_writelane_b32 v253, s7, 15
	s_add_u32 s6, s18, 0x4500
	s_addc_u32 s7, s19, 0
	v_writelane_b32 v253, s6, 16
	s_movk_i32 s61, 0x1110
	s_movk_i32 s84, 0x15ff
	v_writelane_b32 v253, s7, 17
	s_add_u32 s6, s18, 0x4600
	s_addc_u32 s7, s19, 0
	v_writelane_b32 v253, s6, 18
	s_mov_b32 s85, 0xc3e00000
	s_movk_i32 s33, 0xff
	v_writelane_b32 v253, s7, 19
	s_add_u32 s6, s18, 0x4700
	s_addc_u32 s7, s19, 0
	v_writelane_b32 v253, s6, 20
	s_movk_i32 s66, 0x90
	s_mov_b32 s96, 0x2aaaaaab
	v_writelane_b32 v253, s7, 21
	s_add_u32 s6, s18, 0x4800
	s_addc_u32 s7, s19, 0
	v_writelane_b32 v253, s6, 22
	s_movk_i32 s36, 0x190
	s_movk_i32 s37, 0xff40
	v_writelane_b32 v253, s7, 23
	s_add_u32 s6, s18, 0x4900
	s_addc_u32 s7, s19, 0
	v_writelane_b32 v253, s6, 24
	s_movk_i32 s38, 0x567
	s_movk_i32 s39, 0x1500
	v_writelane_b32 v253, s7, 25
	s_add_u32 s6, s18, 0x4a00
	s_addc_u32 s7, s19, 0
	v_writelane_b32 v253, s6, 26
	s_movk_i32 s56, 0x1800
	s_movk_i32 s57, 0xc80
	v_writelane_b32 v253, s7, 27
	s_add_u32 s6, s18, 0x4b00
	s_addc_u32 s7, s19, 0
	v_writelane_b32 v253, s6, 28
	s_movk_i32 s58, 0x3ff
	s_mov_b32 s80, 0xefa18f08
	v_writelane_b32 v253, s7, 29
	s_add_u32 s6, s18, 0x4c00
	s_addc_u32 s7, s19, 0
	v_writelane_b32 v253, s6, 30
	s_mov_b32 s62, 0
	s_mov_b32 s94, 0x3e000000
	v_writelane_b32 v253, s7, 31
	s_add_u32 s6, s18, 0x4d00
	s_addc_u32 s7, s19, 0
	v_writelane_b32 v253, s6, 32
	s_waitcnt lgkmcnt(0)
	s_barrier
; __global__ void __launch_bounds__(NWAVES * 64, 2) mega_fwd(Args A) {
;     ...
;             conv_until(A, lds, l * TL_LAYER + TL_WI2, (G > 96 && bx >= 48) ? ((bx - 48) + (G - 48) < 256 ? 1 : 3) : 0);
	v_writelane_b32 v253, s7, 33
	s_add_u32 s6, s18, 0x4e00
	s_addc_u32 s7, s19, 0
	v_writelane_b32 v253, s6, 34
	s_nop 1
	v_writelane_b32 v253, s7, 35
	s_add_u32 s6, s18, 0x4f00
	s_addc_u32 s7, s19, 0
	v_writelane_b32 v253, s6, 36
	s_nop 1
	v_writelane_b32 v253, s7, 37
	s_add_u32 s6, s18, 0x5000
	s_addc_u32 s7, s19, 0
	v_writelane_b32 v253, s6, 38
	s_nop 1
	v_writelane_b32 v253, s7, 39
	s_add_u32 s6, s18, 0x5100
	s_addc_u32 s7, s19, 0
	v_writelane_b32 v253, s6, 40
	s_nop 1
	v_writelane_b32 v253, s7, 41
	s_add_u32 s6, s18, 0x5200
	s_addc_u32 s7, s19, 0
	v_writelane_b32 v253, s6, 42
	s_nop 1
	v_writelane_b32 v253, s7, 43
	s_add_u32 s6, s18, 0x5300
	s_addc_u32 s7, s19, 0
	v_writelane_b32 v253, s6, 44
	s_nop 1
	v_writelane_b32 v253, s7, 45
	s_add_u32 s6, s18, 0x7400
	s_addc_u32 s7, s19, 0
	v_writelane_b32 v253, s6, 46
	s_nop 1
	v_writelane_b32 v253, s7, 47
	s_add_u32 s6, s18, 0x7500
	s_addc_u32 s7, s19, 0
	v_writelane_b32 v253, s6, 48
	s_cmpk_eq_i32 s95, 0x100
	s_nop 0
	v_writelane_b32 v253, s7, 49
	s_cselect_b64 s[6:7], -1, 0
	s_add_u32 s72, s18, 0x2fe00000
	s_addc_u32 s73, s19, 0
	v_writelane_b32 v253, s6, 50
	s_cmp_lt_i32 s97, 64
	s_nop 0
	v_writelane_b32 v253, s7, 51
	s_cselect_b64 s[6:7], -1, 0
	v_writelane_b32 v253, s6, 52
	s_cmp_gt_i32 s97, 63
	s_nop 0
	v_writelane_b32 v253, s7, 53
	s_cselect_b64 s[6:7], -1, 0
	v_writelane_b32 v253, s6, 54
	s_cmpk_lt_i32 s97, 0x80
	s_nop 0
	v_writelane_b32 v253, s7, 55
	s_cselect_b64 s[6:7], -1, 0
	v_writelane_b32 v253, s6, 56
	s_sub_i32 s3, s97, 64
	s_nop 0
	v_writelane_b32 v253, s7, 57
	s_add_u32 s6, s18, 0x3b602400
	v_writelane_b32 v253, s3, 58
	s_addc_u32 s7, s19, 0
	v_writelane_b32 v253, s6, 59
	s_cmpk_gt_i32 s97, 0x7f
	s_nop 0
	v_writelane_b32 v253, s7, 60
	s_cselect_b64 s[6:7], -1, 0
	s_or_b64 s[0:1], s[6:7], s[0:1]
	v_writelane_b32 v253, s0, 61
	s_nop 1
	v_writelane_b32 v253, s1, 62
	s_and_b32 s0, s69, 3
	s_cmp_lg_u32 s0, 0
	s_cselect_b64 s[0:1], -1, 0
	v_writelane_b32 v253, s0, 63
	s_cmpk_lt_i32 s20, 0x200
	s_nop 0
	v_writelane_b32 v254, s1, 0
	s_cselect_b64 s[0:1], -1, 0
	v_writelane_b32 v254, s0, 1
	s_nop 1
	v_writelane_b32 v254, s1, 2
	s_add_u32 s0, s18, 0x46a00000
	s_addc_u32 s1, s19, 0
	v_writelane_b32 v254, s0, 3
	s_and_b32 s4, s20, 3
	s_nop 0
	v_writelane_b32 v254, s1, 4
	s_mul_i32 s0, s4, 0x12000
	s_add_u32 s0, s34, s0
	v_writelane_b32 v254, s0, 5
	v_writelane_b32 v254, s34, 6
	s_addc_u32 s0, s35, 0
	s_lshl_b32 s68, 2, s4
	v_writelane_b32 v254, s35, 7
	v_writelane_b32 v254, s0, 8
	s_lshl_b32 s1, s20, 4
	s_lshl_b32 s0, s69, 4
	s_add_u32 s22, s18, 0x4fc00000
	v_writelane_b32 v254, s0, 9
	s_addc_u32 s23, s19, 0
	s_lshl_b32 s0, s20, 6
	s_and_b32 s0, s0, 0x7c0
	v_writelane_b32 v254, s1, 10
	s_and_b32 s1, s1, 0xfffff800
	s_or_b32 s0, s1, s0
	s_ashr_i32 s1, s0, 31
	v_writelane_b32 v254, s0, 11
	s_bfe_u32 s3, s20, 0x20005
	s_mov_b32 s35, 0
	v_writelane_b32 v254, s1, 12
	s_mul_i32 s0, s3, 0x60
	v_writelane_b32 v254, s20, 13
	s_add_i32 s1, s0, 0x920
	v_writelane_b32 v254, s1, 14
	v_writelane_b32 v254, s0, 15
	s_bitset1_b32 s0, 11
	s_cmpk_lt_i32 s95, 0x61
	v_writelane_b32 v254, s0, 16
	s_cselect_b64 s[0:1], -1, 0
	s_cmpk_gt_i32 s95, 0x60
	v_writelane_b32 v254, s0, 17
	s_cselect_b64 s[6:7], -1, 0
	s_cmp_lt_i32 s97, 48
	v_writelane_b32 v254, s1, 18
	s_cselect_b64 s[0:1], -1, 0
	v_writelane_b32 v254, s0, 19
	s_cmpk_lt_i32 s97, 0x100
	s_nop 0
	v_writelane_b32 v254, s1, 20
	s_cselect_b64 s[0:1], -1, 0
	v_writelane_b32 v254, s0, 21
	s_nop 1
	v_writelane_b32 v254, s1, 22
	s_sub_i32 s0, s97, 48
	v_writelane_b32 v254, s0, 23
	s_cmpk_lt_i32 s97, 0x130
	s_mul_hi_i32 s0, s97, 0x55555556
	s_cselect_b64 s[8:9], -1, 0
	s_lshr_b32 s1, s0, 31
	s_add_i32 s10, s0, s1
	s_mul_i32 s0, s10, -3
	s_add_i32 s0, s0, s97
	v_writelane_b32 v254, s8, 24
	s_lshl_b32 s1, s0, 13
	s_add_i32 s1, s1, 0x8000
	v_writelane_b32 v254, s9, 25
	v_writelane_b32 v254, s1, 26
	s_sub_i32 s1, s95, 48
	v_writelane_b32 v254, s1, 27
	s_lshl_b32 s8, s10, 5
	s_mul_i32 s1, s10, 0x1c4000
	v_writelane_b32 v254, s8, 28
	s_mul_hi_i32 s8, s8, 0xe200
	s_add_u32 s14, s22, s1
	s_addc_u32 s15, s23, s8
	s_add_u32 s8, s14, 0xe000
	v_writelane_b32 v254, s14, 29
	s_addc_u32 s9, s15, 0
	s_lshl_b32 s1, s10, 9
	s_lshl_b32 s0, s0, 6
	v_writelane_b32 v254, s15, 30
	s_and_b32 s11, s1, 0xfffff800
	s_ashr_i32 s1, s0, 31
	v_writelane_b32 v254, s8, 31
	s_cmp_gt_i32 s97, 47
	s_nop 0
	v_writelane_b32 v254, s9, 32
	s_cselect_b64 s[8:9], -1, 0
	v_writelane_b32 v254, s8, 33
	s_mov_b64 s[14:15], s[6:7]
	s_add_i32 s6, s97, s95
	s_addk_i32 s6, 0xffa0
	v_writelane_b32 v254, s9, 34
	s_cmpk_lt_i32 s6, 0x100
	s_cselect_b32 s8, 3, 5
	v_writelane_b32 v254, s14, 35
	s_and_b64 s[6:7], s[14:15], exec
	s_cselect_b32 s6, s8, 0
	v_writelane_b32 v254, s15, 36
	v_writelane_b32 v254, s6, 37
	s_add_u32 s6, s18, 0x47600000
	v_writelane_b32 v254, s6, 38
	s_addc_u32 s6, s19, 0
	v_writelane_b32 v254, s6, 39
	s_lshl_b32 s14, s95, 5
	s_lshl_b32 s6, s5, 5
	s_cmp_lt_i32 s5, 0
	s_movk_i32 s7, 0xb1
; __global__ void __launch_bounds__(NWAVES * 64, 2) mega_fwd(Args A) {
;     ...
;             { const int rem1 = ((NTOK / 256) * (NWI / 256)) % G;
;               conv_until(A, lds, l * TL_LAYER + (kind == 0 ? TL_WIN : TL_LAYER), (rem1 != 0 && bx >= rem1) ? 3 : 0); }
;             xcd_barrier(bar);
;         } else {
;             const bool std256 = (G == 256);
;             unsigned char* XB8 = ws + WS_X;
; #pragma unroll 1
;             for (int part = 0; part < 3; ++part) {
;                 bool do16, do8; int i16, n16, g8, c8, i8, n8;
;                 if (std256) { do16 = part == 0 || (part == 1 && bx < 64); i16 = part ? 2 : 0; n16 = part ? 1 : 2;
;                               do8 = (part == 1 && bx >= 64) || (part == 2 && bx < 128); g8 = part == 1 ? 192 : 128; c8 = part == 1 ? bx - 64 : bx; i8 = part == 1 ? 0 : 3; n8 = part == 1 ? 2 : 3; }
;                 else { do16 = part == 0; i16 = 0; n16 = 1 << 20; do8 = part == 1; g8 = G; c8 = bx; i8 = 0; n8 = 1 << 20; }
;                 if (do16) { pg8::Gemm g{H, (const bf16*)(wl + LW_WIN), NTOK, C_GATE, DM}; pg8::RangeOrder S; S.init(NTOK, C_GATE, G, bx); S.i0 = i16; S.n = n16;
;                     pg8::EpiProj E{PROJ, NPROJ, (const float*)A.in[7] + (size_t)l * 6144, 1 << 20, ssq, 1.0f};
;                     pg8::gemm_phase<pg8::EpiProj, pg8::RangeOrder, true, true>(lds + RING_OFF, g, S, E); }
;                 if (do8) { pg8::Gemm g{(const bf16*)XB8, (const bf16*)(wl + LW_WIN + WIN8_OFF), NTOK, 6144, DM / 2}; pg8::RangeOrder S; S.init(NTOK, 6144, g8, c8); S.i0 = i8; S.n = n8;
;                     pg8::EpiGate8 E{(unsigned char*)(PROJ + C_GATE), NPROJ * 2, (const float*)A.in[7] + (size_t)l * 6144, ssq, 1.0f / 2048.0f};
;                     pg8::gemm_phase<pg8::EpiGate8, pg8::RangeOrder, true, true, true>(lds + RING_OFF, g, S, E); }
;                 if (part == 1) xcd_barrier(bar);
;                 if (part == 2 && (!std256 || bx >= 128)) { const int mb = std256 ? bx - 128 : bx, ms = std256 ? 128 : G;
;                     if ((ms & 3) == 0) pool_units(lds, PROJ, (const bf16*)(ws + WS_WPT) + (size_t)l * 4 * 192 * 192, Y + (size_t)NTOK * BRW, mb, ms, 512);
;                     else for (int u = mb; u < 512; u += ms) pool_units(lds, PROJ, (const bf16*)(ws + WS_WPT) + (size_t)l * 4 * 192 * 192, Y + (size_t)NTOK * BRW, u, 512, 512);
	s_cselect_b32 s7, s7, 0xb0
	s_mul_i32 s7, s5, s7
	s_mul_i32 s5, s5, 33
	s_cselect_b32 s5, s5, s6
	s_add_i32 s7, s7, s2
	s_mul_hi_i32 s6, s7, 0x2e8ba2e9
	s_lshr_b32 s8, s6, 31
	s_ashr_i32 s6, s6, 6
	s_add_i32 s6, s6, s8
	s_mul_i32 s8, s6, 0x160
	s_sub_i32 s7, s7, s8
	s_bfe_u32 s8, s7, 0x3001c
	s_add_i32 s8, s7, s8
	s_and_b32 s9, s8, 0xfff8
	s_sub_i32 s7, s7, s9
	s_lshl_b32 s6, s6, 3
	s_sext_i32_i16 s8, s8
	s_sext_i32_i16 s7, s7
	s_add_i32 s16, s6, s7
	s_ashr_i32 s6, s8, 3
	v_writelane_b32 v254, s6, 40
	s_lshr_b32 s6, s8, 3
	s_bfe_i64 s[6:7], s[6:7], 0x100000
	s_lshl_b64 s[6:7], s[6:7], 20
	v_writelane_b32 v254, s6, 41
	s_ashr_i32 s17, s16, 31
	s_nop 0
	v_writelane_b32 v254, s7, 42
	s_mov_b32 s6, s16
	v_writelane_b32 v254, s6, 43
	s_nop 1
	v_writelane_b32 v254, s7, 44
	s_lshl_b64 s[6:7], s[16:17], 20
	s_add_u32 s6, s90, s6
	s_addc_u32 s7, s91, s7
	s_add_u32 s8, s6, 0x80000
	s_addc_u32 s9, s7, 0
	v_writelane_b32 v254, s8, 45
	s_nop 1
	v_writelane_b32 v254, s9, 46
	s_add_u32 s8, s6, 0x2000
	v_writelane_b32 v254, s6, 47
	s_addc_u32 s9, s7, 0
	s_add_i32 s2, s5, s2
	s_ashr_i32 s5, s2, 31
	s_lshr_b32 s5, s5, 26
	s_add_i32 s5, s2, s5
	v_writelane_b32 v254, s7, 48
	s_and_b32 s6, s5, 0xffc0
	s_sub_i32 s2, s2, s6
	s_bfe_i32 s6, s2, 0x80000
	s_bfe_u32 s6, s6, 0x3000c
	s_add_i32 s6, s2, s6
	s_and_b32 s7, s6, 0xf8
	s_sub_i32 s2, s2, s7
	s_ashr_i32 s5, s5, 6
	s_lshl_b32 s5, s5, 3
	s_sext_i32_i8 s2, s2
	s_add_i32 s5, s5, s2
	s_bfe_i32 s2, s6, 0x80000
	v_writelane_b32 v254, s8, 49
	s_sext_i32_i16 s2, s2
	s_ashr_i32 s6, s2, 3
	v_writelane_b32 v254, s9, 50
	s_lshr_b32 s2, s2, 3
	v_writelane_b32 v254, s6, 51
	s_bfe_i64 s[6:7], s[2:3], 0x100000
	v_writelane_b32 v254, s6, 52
	s_mul_hi_i32 s2, s5, 0x60000
	s_nop 0
	v_writelane_b32 v254, s7, 53
	v_writelane_b32 v254, s5, 54
	s_mul_i32 s5, s5, 0x60000
	s_add_u32 s6, s12, s5
	s_addc_u32 s7, s13, s2
	s_add_u32 s8, s6, 0x30000
	s_addc_u32 s9, s7, 0
	v_writelane_b32 v254, s8, 55
	s_nop 1
	v_writelane_b32 v254, s9, 56
	s_add_u32 s8, s6, 0x2000
	v_writelane_b32 v254, s6, 57
	s_addc_u32 s9, s7, 0
	s_abs_i32 s2, s95
	v_cvt_f32_u32_e32 v1, s2
	v_writelane_b32 v254, s7, 58
	s_sub_i32 s5, 0, s2
	v_writelane_b32 v254, s8, 59
	v_rcp_iflag_f32_e32 v1, v1
	s_nop 0
	v_writelane_b32 v254, s9, 60
	v_mul_f32_e32 v1, 0x4f7ffffe, v1
	v_cvt_u32_f32_e32 v1, v1
	s_nop 0
	v_readfirstlane_b32 s6, v1
	s_mul_i32 s5, s5, s6
	s_mul_hi_u32 s5, s6, s5
	s_add_i32 s6, s6, s5
	s_mul_hi_u32 s5, s6, 0x580
	s_mul_i32 s5, s5, s2
	s_sub_i32 s5, 0x580, s5
	s_sub_i32 s6, s5, s2
	s_cmp_ge_u32 s5, s2
	s_cselect_b32 s5, s6, s5
	s_sub_i32 s6, s5, s2
	s_cmp_ge_u32 s5, s2
	s_cselect_b32 s2, s6, s5
	s_cmp_lg_u32 s2, 0
	s_cselect_b64 s[6:7], -1, 0
	s_cmp_ge_i32 s97, s2
	s_cselect_b64 s[8:9], -1, 0
	s_and_b64 s[6:7], s[6:7], s[8:9]
	s_mul_i32 s2, s4, 0xc0
	v_writelane_b32 v254, s6, 61
	s_and_b64 s[4:5], s[6:7], exec
	s_cselect_b32 s4, 3, 0
	v_writelane_b32 v254, s7, 62
	v_writelane_b32 v255, s2, 0
	s_lshl_b32 s2, s2, 1
	v_writelane_b32 v254, s4, 63
	s_add_u32 s4, s88, s2
	s_addc_u32 s5, s89, 0
	v_writelane_b32 v255, s4, 1
	s_and_b32 s2, s10, 3
	s_mulk_i32 s2, 0x300
	v_writelane_b32 v255, s5, 2
	s_mul_i32 s4, s11, 0xc00
	s_lshl_b32 s5, s97, 6
	s_or_b32 s2, s4, s2
	s_lshl_b64 s[0:1], s[0:1], 2
	v_writelane_b32 v255, s5, 3
	s_lshl_b32 s5, s95, 6
	s_mul_hi_i32 s4, s11, 0xc00
	s_add_u32 s0, s2, s0
	s_addc_u32 s1, s4, s1
	s_add_u32 s0, s18, s0
	v_writelane_b32 v255, s5, 4
	s_addc_u32 s1, s19, s1
	v_writelane_b32 v255, s0, 5
	s_mul_i32 s2, s95, 0x18000
	s_add_i32 s93, 0, 0x20180
	v_writelane_b32 v255, s1, 6
	s_mul_i32 s0, s3, 0xc0
	s_mul_hi_i32 s3, s14, 0xc00
	v_writelane_b32 v255, s2, 7
	s_lshl_b32 s1, s97, 9
	s_lshl_b32 s0, s0, 1
	v_writelane_b32 v255, s3, 8
	s_mul_i32 s2, s95, 0xa8000
	v_writelane_b32 v255, s14, 9
	s_mul_hi_i32 s3, s14, 0x5400
	v_writelane_b32 v255, s2, 10
	s_add_i32 s60, 0, 0x20184
	v_mov_b32_e32 v1, 0x358637bd
	v_writelane_b32 v255, s3, 11
	v_writelane_b32 v255, s1, 12
	s_lshl_b32 s1, s95, 11
	v_writelane_b32 v255, s1, 13
	s_lshl_b32 s1, s95, 4
	v_writelane_b32 v255, s1, 14
	s_lshl_b32 s1, s95, 10
	v_writelane_b32 v255, s1, 15
	s_lshl_b32 s1, s95, 9
	v_writelane_b32 v255, s1, 16
	s_add_i32 s1, 0, 0x20160
	v_writelane_b32 v255, s1, 17
	s_add_i32 s1, 0, 0x20164
	v_writelane_b32 v255, s1, 18
	s_add_i32 s1, 0, 0x2d00
	v_writelane_b32 v255, s1, 19
	v_writelane_b32 v255, s0, 20
	s_add_i32 s64, 0, 0x12600
	s_nop 0
	v_writelane_b32 v255, s1, 21
	s_add_i32 s0, 0, 0xf000
	v_writelane_b32 v255, s0, 22
	s_add_i32 s0, 0, 0x8800
	v_writelane_b32 v255, s0, 23
	v_writelane_b32 v255, s90, 24
	s_nop 1
	v_writelane_b32 v255, s91, 25
	v_writelane_b32 v255, s69, 26
	v_writelane_b32 v255, s88, 27
	s_nop 1
	v_writelane_b32 v255, s89, 28
	v_writelane_b32 v255, s21, 29
	v_writelane_b32 v255, s22, 30
	v_writelane_b32 v255, s23, 31
	v_writelane_b32 v255, s93, 32
	v_writelane_b32 v255, s60, 33
	v_writelane_b32 v255, s92, 34
	s_nop 1
	v_writelane_b32 v255, s93, 35
	s_branch .LBB0_287

; #define LAS __attribute__((address_space(3)))
; __device__ __forceinline__ void att_unit(LAS unsigned char* lds, const bf16* PROJ, const float* COS, const float* SIN, const float* sinks, bf16* YA, int u) {
;     ...
;     for (int idx = tid; idx < 256 * 8; idx += 512) { const int ch = idx >> 8, kk = idx & 255;
;         v4u w = (v4u){0u, 0u, 0u, 0u};
;         if (kk >= kk0) w = *(const v4u*)(PROJ + (size_t)(tok0 + kk) * NPROJ + C_VA + kvh * 64 + ch * 8);
;         LAS bf16* vp = VT + (ch * 8) * 264 + kk;
;         vp[0 * 264] = (bf16)(w.x & 0xffffu); vp[1 * 264] = (bf16)(w.x >> 16); vp[2 * 264] = (bf16)(w.y & 0xffffu); vp[3 * 264] = (bf16)(w.y >> 16);
;         vp[4 * 264] = (bf16)(w.z & 0xffffu); vp[5 * 264] = (bf16)(w.z >> 16); vp[6 * 264] = (bf16)(w.w & 0xffffu); vp[7 * 264] = (bf16)(w.w >> 16); }
.LBB0_911:
	s_or_b64 exec, exec, s[0:1]
	s_movk_i32 s0, 0x800
	v_cmp_gt_i32_e32 vcc, s0, v28
	s_and_saveexec_b64 s[2:3], vcc
	s_cbranch_execz .LBB0_916
	v_and_b32_e32 v2, 0xff, v28
	v_add_u32_e32 v6, s7, v2
	v_mov_b64_e32 v[4:5], s[88:89]
	v_mad_i64_i32 v[4:5], s[0:1], v6, s77, v[4:5]
	s_lshl_b32 s34, s6, 7
	v_cmp_le_u32_e32 vcc, s41, v2
	v_lshl_add_u64 v[8:9], v[4:5], 0, s[34:35]
	v_lshl_add_u32 v2, v2, 1, 0
	v_ashrrev_i32_e32 v11, 8, v28
	v_mov_b32_e32 v76, 0
	v_mov_b32_e32 v77, 0
	v_mov_b32_e32 v78, 0
	v_mov_b32_e32 v79, 0
	v_mov_b32_e32 v80, 0
	v_mov_b32_e32 v81, 0
	v_mov_b32_e32 v82, 0
	v_mov_b32_e32 v83, 0
	v_mov_b32_e32 v84, 0
	v_mov_b32_e32 v85, 0
	v_mov_b32_e32 v86, 0
	v_mov_b32_e32 v87, 0
	v_mov_b32_e32 v88, 0
	v_mov_b32_e32 v89, 0
	v_mov_b32_e32 v90, 0
	v_mov_b32_e32 v91, 0
	s_and_saveexec_b64 s[0:1], vcc
	s_cbranch_execz .Lvt_skip
	v_lshlrev_b32_e32 v4, 4, v11
	v_mov_b32_e32 v5, 0
	v_lshl_add_u64 v[4:5], v[8:9], 0, v[4:5]
	global_load_dwordx4 v[76:79], v[4:5], off offset:2048
	global_load_dwordx4 v[80:83], v[4:5], off offset:2080
	global_load_dwordx4 v[84:87], v[4:5], off offset:2112
	global_load_dwordx4 v[88:91], v[4:5], off offset:2144
.Lvt_skip:
	s_or_b64 exec, exec, s[0:1]
	s_movk_i32 s0, 0x1080
	v_mad_i32_i24 v11, v11, s0, v2
	v_add_u32_e32 v92, 0x6300, v11
	s_waitcnt vmcnt(0)
	ds_write_b16 v11, v76 offset:36864
	ds_write_b16_d16_hi v11, v76 offset:37392
	ds_write_b16 v11, v77 offset:37920
	ds_write_b16_d16_hi v11, v77 offset:38448
	ds_write_b16 v11, v78 offset:38976
	ds_write_b16_d16_hi v11, v78 offset:39504
	ds_write_b16 v11, v79 offset:40032
	ds_write_b16_d16_hi v11, v79 offset:40560
	ds_write_b16 v11, v80 offset:45312
	ds_write_b16_d16_hi v11, v80 offset:45840
	ds_write_b16 v11, v81 offset:46368
	ds_write_b16_d16_hi v11, v81 offset:46896
	ds_write_b16 v11, v82 offset:47424
	ds_write_b16_d16_hi v11, v82 offset:47952
	ds_write_b16 v11, v83 offset:48480
	ds_write_b16_d16_hi v11, v83 offset:49008
	ds_write_b16 v11, v84 offset:53760
	ds_write_b16_d16_hi v11, v84 offset:54288
	ds_write_b16 v11, v85 offset:54816
	ds_write_b16_d16_hi v11, v85 offset:55344
	ds_write_b16 v11, v86 offset:55872
	ds_write_b16_d16_hi v11, v86 offset:56400
	ds_write_b16 v11, v87 offset:56928
	ds_write_b16_d16_hi v11, v87 offset:57456
	ds_write_b16 v92, v88 offset:36864
	ds_write_b16_d16_hi v92, v88 offset:37392
	ds_write_b16 v92, v89 offset:37920
	ds_write_b16_d16_hi v92, v89 offset:38448
	ds_write_b16 v92, v90 offset:38976
	ds_write_b16_d16_hi v92, v90 offset:39504
	ds_write_b16 v92, v91 offset:40032
	ds_write_b16_d16_hi v92, v91 offset:40560
